# attention tile body rewritten (K frag reads pipelined, mask 2 ops, prefetch waits moved to first use) + six weight transposes moved from PH0 into the idle workgroups of the in-projection tail
# speedup vs baseline: 1.0005x; 1.0005x over previous
; __global__ void __launch_bounds__(512, 2) fwd_megakernel(Args args) {
;     ...
;             constexpr int I0 = 32 * 164, I1 = 32 * 16, I2 = 16 * 32, I3 = 8 * 32, I4 = 8 * 32, I5 = 32 * 32, I6 = 32 * 128, I7 = 128 * 32;
;             constexpr int NIT = I0 + I1 + I2 + I3 + I4 + I5 + I6 + I7;
;             for (int it = gw; it < NIT; it += NGW) {
;                 int r = it;
;                 if (r < I0) { transpose_item<true>(w_in, 2048, NIN, 164, WT_IN, 0, scr, r, lane); continue; } r -= I0;
;                 if (r < I1) { transpose_item<false>(w_mem_kv, 2048, 1024, 16, WT_IN, NPAD, scr, r, lane); continue; } r -= I1;
;                 if (r < I2) { transpose_item<false>(w_attn_o, 1024, 2048, 32, WT_AO, 0, scr, r, lane); continue; } r -= I2;
;                 if (r < I3) { transpose_item<false>(w_mem_o, 512, 2048, 32, WT_MO, 0, scr, r, lane); continue; } r -= I3;
;                 if (r < I4) { transpose_item<false>(w_conv_o, 512, 2048, 32, WT_CO, 0, scr, r, lane); continue; } r -= I4;
;                 if (r < I5) { transpose_item<false>(w_out, 2048, 2048, 32, WT_OUT, 0, scr, r, lane); continue; } r -= I5;
;                 if (r < I6) { transpose_item<false>(w_up, 2048, 8192, 128, WT_UP, 0, scr, r, lane); continue; } r -= I6;
;                 transpose_item<false>(w_down, 8192, 2048, 32, WT_DN, 0, scr, r, lane);
;             }
.LBB0_24:
	s_add_i32 s16, s16, s96
	s_add_i32 s11, s11, s12
	s_add_i32 s13, s13, s14
	s_add_i32 s10, s10, s15
	s_cmpk_gt_i32 s16, 0x167f
	s_cbranch_scc1 .LBB0_68
.LBB0_25:
	s_cmpk_gt_i32 s16, 0x147f
	s_mov_b64 s[2:3], -1
	s_cbranch_scc0 .LBB0_51
	s_sub_i32 s70, s16, 0x1480
	s_lshr_b32 s2, s70, 4
	s_and_b32 s3, s70, 15
	s_lshl_b32 s6, s2, 18
	s_lshl_b32 s7, s3, 8
	s_add_u32 s17, s6, s7
	s_lshl_b32 s3, s3, 18
	s_lshl_b32 s2, s2, 7
	s_add_u32 s7, s3, s2
	s_add_u32 s7, s7, 0x2900000
	s_add_u32 s2, s44, s17
	s_addc_u32 s3, s45, 0
	s_add_u32 s6, s30, s7
	s_addc_u32 s7, s31, 0
	s_mov_b32 s70, 0x4000
	s_mov_b32 vcc_lo, 0x8000

; #define LAS __attribute__((address_space(3)))
; template <bool INMAP>
; DI void transpose_item(const float* W, int K, int N, int nblk, bf16_t* WT, int row_off, LAS float* scr, int item, int lane) {
;     const int kb = item / nblk, nb = item % nblk, k0 = 64 * kb, n0 = 64 * nb;
;     const int q = lane & 15, kr = lane >> 4;
;     const int np = n0 + 4 * q;
;     int ns = np;
;     if (INMAP) ns = np < 2640 ? np : (np < 2816 ? -1 : np - 176);
; __global__ void __launch_bounds__(512, 2) fwd_megakernel(Args args) {
;     ...
;             for (int it = gw; it < NIT; it += NGW) {
;                 int r = it;
;                 if (r < I0) { transpose_item<true>(w_in, 2048, NIN, 164, WT_IN, 0, scr, r, lane); continue; } r -= I0;
;                 if (r < I1) { transpose_item<false>(w_mem_kv, 2048, 1024, 16, WT_IN, NPAD, scr, r, lane); continue; } r -= I1;
;                 if (r < I2) { transpose_item<false>(w_attn_o, 1024, 2048, 32, WT_AO, 0, scr, r, lane); continue; } r -= I2;
;                 if (r < I3) { transpose_item<false>(w_mem_o, 512, 2048, 32, WT_MO, 0, scr, r, lane); continue; } r -= I3;
;                 if (r < I4) { transpose_item<false>(w_conv_o, 512, 2048, 32, WT_CO, 0, scr, r, lane); continue; } r -= I4;
;                 if (r < I5) { transpose_item<false>(w_out, 2048, 2048, 32, WT_OUT, 0, scr, r, lane); continue; } r -= I5;
;                 if (r < I6) { transpose_item<false>(w_up, 2048, 8192, 128, WT_UP, 0, scr, r, lane); continue; } r -= I6;
;                 transpose_item<false>(w_down, 8192, 2048, 32, WT_DN, 0, scr, r, lane);
.LBB0_287:
	s_cmp_lt_u32 s86, 80
	s_cbranch_scc1 .Lmytail_done
	v_readlane_b32 s49, v255, 24
	v_readlane_b32 s34, v252, 34
	v_readlane_b32 s35, v252, 35
	s_lshl_b32 s2, s49, 23
	s_add_u32 s34, s34, s2
	s_addc_u32 s35, s35, 0
	v_readlane_b32 s36, v252, 36
	v_readlane_b32 s37, v252, 37
	s_lshl_b32 s2, s49, 22
	s_add_u32 s36, s36, s2
	s_addc_u32 s37, s37, 0
	v_readlane_b32 s38, v252, 38
	v_readlane_b32 s39, v252, 39
	s_lshl_b32 s2, s49, 22
	s_add_u32 s38, s38, s2
	s_addc_u32 s39, s39, 0
	v_readlane_b32 s40, v252, 42
	v_readlane_b32 s41, v252, 43
	s_lshl_b32 s2, s49, 24
	s_add_u32 s40, s40, s2
	s_addc_u32 s41, s41, 0
	v_readlane_b32 s42, v252, 46
	v_readlane_b32 s43, v252, 47
	s_lshl_b32 s2, s49, 26
	s_add_u32 s42, s42, s2
	s_addc_u32 s43, s43, 0
	s_mov_b64 s[44:45], s[60:61]
	s_lshl_b32 s2, s49, 26
	s_add_u32 s44, s44, s2
	s_addc_u32 s45, s45, 0
	s_mov_b64 s[46:47], s[64:65]
	v_readfirstlane_b32 s2, v186
	v_and_b32_e32 v8, 63, v186
	s_lshr_b32 s2, s2, 6
	s_mul_i32 s6, s2, 0x4100
	s_sub_i32 s3, s86, 80
	s_lshl_b32 s3, s3, 3
	s_add_i32 s16, s3, s2
	s_addk_i32 s16, 0x1680
	s_movk_i32 s48, 0x580
	v_and_b32_e32 v9, 15, v8
	v_lshlrev_b32_e32 v9, 2, v9
	v_lshrrev_b32_e32 v27, 3, v8
	v_lshrrev_b32_e32 v29, 4, v8
	v_and_b32_e32 v0, 7, v8
	v_mul_u32_u24_e32 v0, 0x820, v0
	v_lshlrev_b32_e32 v1, 2, v27
	v_add3_u32 v28, s6, v0, v1
	v_mul_u32_u24_e32 v0, 0x104, v29
	v_lshl_add_u32 v1, v9, 2, s6
	v_add_u32_e32 v54, v1, v0
	s_cmpk_gt_u32 s16, 0x3e7f
	s_cbranch_scc1 .Lmytail_done
.Lmytail_loop:
	s_cmpk_gt_u32 s16, 0x187f
	s_cbranch_scc1 .Lmytail_ge_memo
	s_sub_i32 s70, s16, 0x1680
	s_lshr_b32 s2, s70, 5
	s_and_b32 s3, s70, 31
	s_lshl_b32 s6, s2, 19
	s_lshl_b32 s7, s3, 8
	s_add_u32 s17, s6, s7
	s_lshl_b32 s3, s3, 17
	s_lshl_b32 s2, s2, 7
	s_add_u32 s7, s3, s2
	s_add_u32 s7, s7, 0x2d00000
	s_add_u32 s2, s34, s17
	s_addc_u32 s3, s35, 0
	s_add_u32 s6, s46, s7
	s_addc_u32 s7, s47, 0
	s_mov_b32 s70, 0x8000
	s_mov_b32 vcc_lo, 0x4000
	s_branch .Lmytail_body
.Lmytail_ge_memo:
	s_cmpk_gt_u32 s16, 0x197f
	s_cbranch_scc1 .Lmytail_ge_convo
	s_sub_i32 s70, s16, 0x1880
	s_lshr_b32 s2, s70, 5
	s_and_b32 s3, s70, 31
	s_lshl_b32 s6, s2, 19
	s_lshl_b32 s7, s3, 8
	s_add_u32 s17, s6, s7
	s_lshl_b32 s3, s3, 16
	s_lshl_b32 s2, s2, 7
	s_add_u32 s7, s3, s2
	s_add_u32 s7, s7, 0x3100000
	s_add_u32 s2, s36, s17
	s_addc_u32 s3, s37, 0
	s_add_u32 s6, s46, s7
	s_addc_u32 s7, s47, 0
	s_mov_b32 s70, 0x8000
	s_mov_b32 vcc_lo, 0x2000
	s_branch .Lmytail_body
.Lmytail_ge_convo:
	s_cmpk_gt_u32 s16, 0x1a7f
	s_cbranch_scc1 .Lmytail_ge_out
	s_sub_i32 s70, s16, 0x1980
	s_lshr_b32 s2, s70, 5
	s_and_b32 s3, s70, 31
	s_lshl_b32 s6, s2, 19
	s_lshl_b32 s7, s3, 8
	s_add_u32 s17, s6, s7
	s_lshl_b32 s3, s3, 16
	s_lshl_b32 s2, s2, 7
	s_add_u32 s7, s3, s2
	s_add_u32 s7, s7, 0x3300000
	s_add_u32 s2, s38, s17
	s_addc_u32 s3, s39, 0
	s_add_u32 s6, s46, s7
	s_addc_u32 s7, s47, 0
	s_mov_b32 s70, 0x8000
	s_mov_b32 vcc_lo, 0x2000
	s_branch .Lmytail_body
.Lmytail_ge_out:
	s_cmpk_gt_u32 s16, 0x1e7f
	s_cbranch_scc1 .Lmytail_ge_up
	s_sub_i32 s70, s16, 0x1a80
	s_lshr_b32 s2, s70, 5
	s_and_b32 s3, s70, 31
	s_lshl_b32 s6, s2, 19
	s_lshl_b32 s7, s3, 8
	s_add_u32 s17, s6, s7
	s_lshl_b32 s3, s3, 18
	s_lshl_b32 s2, s2, 7
	s_add_u32 s7, s3, s2
	s_add_u32 s7, s7, 0x3500000
	s_add_u32 s2, s40, s17
	s_addc_u32 s3, s41, 0
	s_add_u32 s6, s46, s7
	s_addc_u32 s7, s47, 0
	s_mov_b32 s70, 0x8000
	s_mov_b32 vcc_lo, 0x8000
	s_branch .Lmytail_body
.Lmytail_ge_up:
	s_cmpk_gt_u32 s16, 0x2e7f
	s_cbranch_scc1 .Lmytail_ge_down
	s_sub_i32 s70, s16, 0x1e80
	s_lshr_b32 s2, s70, 7
	s_and_b32 s3, s70, 127
	s_lshl_b32 s6, s2, 21
	s_lshl_b32 s7, s3, 8
	s_add_u32 s17, s6, s7
	s_lshl_b32 s3, s3, 18
	s_lshl_b32 s2, s2, 7
	s_add_u32 s7, s3, s2
	s_add_u32 s7, s7, 0x3d00000
	s_add_u32 s2, s42, s17
	s_addc_u32 s3, s43, 0
	s_add_u32 s6, s46, s7
	s_addc_u32 s7, s47, 0
	s_mov_b32 s70, 0x20000
	s_mov_b32 vcc_lo, 0x8000
	s_branch .Lmytail_body
.Lmytail_ge_down:
	s_sub_i32 s70, s16, 0x2e80
	s_lshr_b32 s2, s70, 5
	s_and_b32 s3, s70, 31
	s_lshl_b32 s6, s2, 19
	s_lshl_b32 s7, s3, 8
	s_add_u32 s17, s6, s7
	s_lshl_b32 s3, s3, 20
	s_lshl_b32 s2, s2, 7
	s_add_u32 s7, s3, s2
	s_add_u32 s7, s7, 0x5d00000
	s_add_u32 s2, s44, s17
	s_addc_u32 s3, s45, 0
	s_add_u32 s6, s46, s7
	s_addc_u32 s7, s47, 0
	s_mov_b32 s70, 0x8000
	s_mov_b32 vcc_lo, 0x20000
; #define LAS __attribute__((address_space(3)))
; template <bool INMAP>
; DI void transpose_item(const float* W, int K, int N, int nblk, bf16_t* WT, int row_off, LAS float* scr, int item, int lane) {
;     ...
; #pragma unroll 16
;     for (int i = 0; i < 16; ++i) { const int kk = 4 * i + kr;
;         f32x4 v = {0.f, 0.f, 0.f, 0.f};
;         if (ns >= 0) v = __builtin_nontemporal_load((const f32x4*)(W + (size_t)(k0 + kk) * N + ns));
;         LAS float* d = scr + kk * 65 + 4 * q; d[0] = v.x; d[1] = v.y; d[2] = v.z; d[3] = v.w; }
;     asm volatile("s_waitcnt lgkmcnt(0)" ::: "memory");
.Lmytail_body:
	v_mul_u32_u24_e32 v180, s70, v29
	v_mul_u32_u24_e32 v181, vcc_lo, v27
	v_and_b32_e32 v182, 7, v8
	v_lshrrev_b32_e32 v180, 2, v180
	v_lshrrev_b32_e32 v181, 3, v181
	v_lshl_add_u32 v180, v9, 2, v180
	v_lshl_add_u32 v181, v182, 4, v181
	global_load_dwordx4 v[194:197], v180, s[2:3] nt
	s_add_u32 s2, s2, s70
	s_addc_u32 s3, s3, 0
	global_load_dwordx4 v[198:201], v180, s[2:3] nt
	s_add_u32 s2, s2, s70
	s_addc_u32 s3, s3, 0
	global_load_dwordx4 v[202:205], v180, s[2:3] nt
	s_add_u32 s2, s2, s70
	s_addc_u32 s3, s3, 0
	global_load_dwordx4 v[206:209], v180, s[2:3] nt
	s_add_u32 s2, s2, s70
	s_addc_u32 s3, s3, 0
	global_load_dwordx4 v[210:213], v180, s[2:3] nt
	s_add_u32 s2, s2, s70
	s_addc_u32 s3, s3, 0
	global_load_dwordx4 v[214:217], v180, s[2:3] nt
	s_add_u32 s2, s2, s70
	s_addc_u32 s3, s3, 0
	global_load_dwordx4 v[218:221], v180, s[2:3] nt
	s_add_u32 s2, s2, s70
	s_addc_u32 s3, s3, 0
	global_load_dwordx4 v[222:225], v180, s[2:3] nt
	s_add_u32 s2, s2, s70
	s_addc_u32 s3, s3, 0
	global_load_dwordx4 v[226:229], v180, s[2:3] nt
	s_add_u32 s2, s2, s70
	s_addc_u32 s3, s3, 0
	global_load_dwordx4 v[230:233], v180, s[2:3] nt
	s_add_u32 s2, s2, s70
	s_addc_u32 s3, s3, 0
	global_load_dwordx4 v[234:237], v180, s[2:3] nt
	s_add_u32 s2, s2, s70
	s_addc_u32 s3, s3, 0
	global_load_dwordx4 v[238:241], v180, s[2:3] nt
	s_add_u32 s2, s2, s70
	s_addc_u32 s3, s3, 0
	global_load_dwordx4 v[242:245], v180, s[2:3] nt
	s_add_u32 s2, s2, s70
	s_addc_u32 s3, s3, 0
	global_load_dwordx4 v[246:249], v180, s[2:3] nt
	s_add_u32 s2, s2, s70
	s_addc_u32 s3, s3, 0
	global_load_dwordx4 v[0:3], v180, s[2:3] nt
	s_add_u32 s2, s2, s70
	s_addc_u32 s3, s3, 0
	global_load_dwordx4 v[4:7], v180, s[2:3] nt
	s_waitcnt vmcnt(15)
	ds_write2_b32 v54, v194, v195 offset1:1
	ds_write2_b32 v54, v196, v197 offset0:2 offset1:3
	v_add_u32_e32 v183, 0x410, v54
	s_waitcnt vmcnt(14)
	ds_write2_b32 v183, v198, v199 offset1:1
	ds_write2_b32 v183, v200, v201 offset0:2 offset1:3
	v_add_u32_e32 v182, 0x820, v54
	s_waitcnt vmcnt(13)
	ds_write2_b32 v182, v202, v203 offset1:1
	ds_write2_b32 v182, v204, v205 offset0:2 offset1:3
	v_add_u32_e32 v183, 0xc30, v54
	s_waitcnt vmcnt(12)
	ds_write2_b32 v183, v206, v207 offset1:1
	ds_write2_b32 v183, v208, v209 offset0:2 offset1:3
	v_add_u32_e32 v182, 0x1040, v54
	s_waitcnt vmcnt(11)
	ds_write2_b32 v182, v210, v211 offset1:1
	ds_write2_b32 v182, v212, v213 offset0:2 offset1:3
	v_add_u32_e32 v183, 0x1450, v54
	s_waitcnt vmcnt(10)
	ds_write2_b32 v183, v214, v215 offset1:1
	ds_write2_b32 v183, v216, v217 offset0:2 offset1:3
	v_add_u32_e32 v182, 0x1860, v54
	s_waitcnt vmcnt(9)
	ds_write2_b32 v182, v218, v219 offset1:1
	ds_write2_b32 v182, v220, v221 offset0:2 offset1:3
	v_add_u32_e32 v183, 0x1c70, v54
	s_waitcnt vmcnt(8)
	ds_write2_b32 v183, v222, v223 offset1:1
	ds_write2_b32 v183, v224, v225 offset0:2 offset1:3
	v_add_u32_e32 v182, 0x2080, v54
	s_waitcnt vmcnt(7)
	ds_write2_b32 v182, v226, v227 offset1:1
	ds_write2_b32 v182, v228, v229 offset0:2 offset1:3
	v_add_u32_e32 v183, 0x2490, v54
	s_waitcnt vmcnt(6)
	ds_write2_b32 v183, v230, v231 offset1:1
	ds_write2_b32 v183, v232, v233 offset0:2 offset1:3
	v_add_u32_e32 v182, 0x28a0, v54
	s_waitcnt vmcnt(5)
	ds_write2_b32 v182, v234, v235 offset1:1
	ds_write2_b32 v182, v236, v237 offset0:2 offset1:3
	v_add_u32_e32 v183, 0x2cb0, v54
	s_waitcnt vmcnt(4)
	ds_write2_b32 v183, v238, v239 offset1:1
	ds_write2_b32 v183, v240, v241 offset0:2 offset1:3
	v_add_u32_e32 v182, 0x30c0, v54
	s_waitcnt vmcnt(3)
	ds_write2_b32 v182, v242, v243 offset1:1
	ds_write2_b32 v182, v244, v245 offset0:2 offset1:3
	v_add_u32_e32 v183, 0x34d0, v54
	s_waitcnt vmcnt(2)
	ds_write2_b32 v183, v246, v247 offset1:1
	ds_write2_b32 v183, v248, v249 offset0:2 offset1:3
	v_add_u32_e32 v182, 0x38e0, v54
	s_waitcnt vmcnt(1)
	ds_write2_b32 v182, v0, v1 offset1:1
	ds_write2_b32 v182, v2, v3 offset0:2 offset1:3
	v_add_u32_e32 v183, 0x3cf0, v54
	s_waitcnt vmcnt(0)
	ds_write2_b32 v183, v4, v5 offset1:1
	ds_write2_b32 v183, v6, v7 offset0:2 offset1:3
	s_waitcnt lgkmcnt(0)
; #define LAS __attribute__((address_space(3)))
; DI unsigned pk2(float lo, float hi) { f32x2 v = {lo, hi}; bf16x2_t b = __builtin_convertvector(v, bf16x2_t); return __builtin_bit_cast(unsigned, b); }
; template <bool INMAP>
; DI void transpose_item(const float* W, int K, int N, int nblk, bf16_t* WT, int row_off, LAS float* scr, int item, int lane) {
;     ...
;     asm volatile("s_waitcnt lgkmcnt(0)" ::: "memory");
;     const int c = lane & 7;
; #pragma unroll
;     for (int j = 0; j < 8; ++j) { const int n = (lane >> 3) + 8 * j; const LAS float* s = scr + (8 * c) * 65 + n;
;         u32x4 o; o.x = pk2(s[0 * 65], s[1 * 65]); o.y = pk2(s[2 * 65], s[3 * 65]); o.z = pk2(s[4 * 65], s[5 * 65]); o.w = pk2(s[6 * 65], s[7 * 65]);
;         *(u32x4*)(WT + (size_t)(row_off + n0 + n) * K + k0 + 8 * c) = o; }
;     asm volatile("s_waitcnt lgkmcnt(0)" ::: "memory");
	ds_read_b32 v194, v28 offset:0
	ds_read_b32 v195, v28 offset:260
	ds_read_b32 v196, v28 offset:520
	ds_read_b32 v197, v28 offset:780
	ds_read_b32 v198, v28 offset:1040
	ds_read_b32 v199, v28 offset:1300
	ds_read_b32 v200, v28 offset:1560
	ds_read_b32 v201, v28 offset:1820
	ds_read_b32 v202, v28 offset:32
	ds_read_b32 v203, v28 offset:292
	ds_read_b32 v204, v28 offset:552
	ds_read_b32 v205, v28 offset:812
	ds_read_b32 v206, v28 offset:1072
	ds_read_b32 v207, v28 offset:1332
	ds_read_b32 v208, v28 offset:1592
	ds_read_b32 v209, v28 offset:1852
	ds_read_b32 v210, v28 offset:64
	ds_read_b32 v211, v28 offset:324
	ds_read_b32 v212, v28 offset:584
	ds_read_b32 v213, v28 offset:844
	ds_read_b32 v214, v28 offset:1104
	ds_read_b32 v215, v28 offset:1364
	ds_read_b32 v216, v28 offset:1624
	ds_read_b32 v217, v28 offset:1884
	ds_read_b32 v218, v28 offset:96
	ds_read_b32 v219, v28 offset:356
	ds_read_b32 v220, v28 offset:616
	ds_read_b32 v221, v28 offset:876
	ds_read_b32 v222, v28 offset:1136
	ds_read_b32 v223, v28 offset:1396
	ds_read_b32 v224, v28 offset:1656
	ds_read_b32 v225, v28 offset:1916
	ds_read_b32 v226, v28 offset:128
	ds_read_b32 v227, v28 offset:388
	ds_read_b32 v228, v28 offset:648
	ds_read_b32 v229, v28 offset:908
	ds_read_b32 v230, v28 offset:1168
	ds_read_b32 v231, v28 offset:1428
	ds_read_b32 v232, v28 offset:1688
	ds_read_b32 v233, v28 offset:1948
	ds_read_b32 v234, v28 offset:160
	ds_read_b32 v235, v28 offset:420
	ds_read_b32 v236, v28 offset:680
	ds_read_b32 v237, v28 offset:940
	ds_read_b32 v238, v28 offset:1200
	ds_read_b32 v239, v28 offset:1460
	ds_read_b32 v240, v28 offset:1720
	ds_read_b32 v241, v28 offset:1980
	ds_read_b32 v242, v28 offset:192
	ds_read_b32 v243, v28 offset:452
	ds_read_b32 v244, v28 offset:712
	ds_read_b32 v245, v28 offset:972
	ds_read_b32 v246, v28 offset:1232
	ds_read_b32 v247, v28 offset:1492
	ds_read_b32 v248, v28 offset:1752
	ds_read_b32 v249, v28 offset:2012
	ds_read_b32 v0, v28 offset:224
	ds_read_b32 v1, v28 offset:484
	ds_read_b32 v2, v28 offset:744
	ds_read_b32 v3, v28 offset:1004
	ds_read_b32 v4, v28 offset:1264
	ds_read_b32 v5, v28 offset:1524
	ds_read_b32 v6, v28 offset:1784
	ds_read_b32 v7, v28 offset:2044
	s_waitcnt lgkmcnt(15)
	v_cvt_pk_bf16_f32 v194, v194, v195
	v_cvt_pk_bf16_f32 v195, v196, v197
	v_cvt_pk_bf16_f32 v196, v198, v199
	v_cvt_pk_bf16_f32 v197, v200, v201
	global_store_dwordx4 v181, v[194:197], s[6:7]
	s_add_u32 s6, s6, vcc_lo
	s_addc_u32 s7, s7, 0
	v_cvt_pk_bf16_f32 v202, v202, v203
	v_cvt_pk_bf16_f32 v203, v204, v205
	v_cvt_pk_bf16_f32 v204, v206, v207
	v_cvt_pk_bf16_f32 v205, v208, v209
	global_store_dwordx4 v181, v[202:205], s[6:7]
	s_add_u32 s6, s6, vcc_lo
	s_addc_u32 s7, s7, 0
	v_cvt_pk_bf16_f32 v210, v210, v211
	v_cvt_pk_bf16_f32 v211, v212, v213
	v_cvt_pk_bf16_f32 v212, v214, v215
	v_cvt_pk_bf16_f32 v213, v216, v217
	global_store_dwordx4 v181, v[210:213], s[6:7]
	s_add_u32 s6, s6, vcc_lo
	s_addc_u32 s7, s7, 0
	v_cvt_pk_bf16_f32 v218, v218, v219
	v_cvt_pk_bf16_f32 v219, v220, v221
	v_cvt_pk_bf16_f32 v220, v222, v223
	v_cvt_pk_bf16_f32 v221, v224, v225
	global_store_dwordx4 v181, v[218:221], s[6:7]
	s_add_u32 s6, s6, vcc_lo
	s_addc_u32 s7, s7, 0
	v_cvt_pk_bf16_f32 v226, v226, v227
	v_cvt_pk_bf16_f32 v227, v228, v229
	v_cvt_pk_bf16_f32 v228, v230, v231
	v_cvt_pk_bf16_f32 v229, v232, v233
	global_store_dwordx4 v181, v[226:229], s[6:7]
	s_add_u32 s6, s6, vcc_lo
	s_addc_u32 s7, s7, 0
	v_cvt_pk_bf16_f32 v234, v234, v235
	v_cvt_pk_bf16_f32 v235, v236, v237
	v_cvt_pk_bf16_f32 v236, v238, v239
	v_cvt_pk_bf16_f32 v237, v240, v241
	global_store_dwordx4 v181, v[234:237], s[6:7]
	s_add_u32 s6, s6, vcc_lo
	s_addc_u32 s7, s7, 0
	s_waitcnt lgkmcnt(8)
	v_cvt_pk_bf16_f32 v242, v242, v243
	v_cvt_pk_bf16_f32 v243, v244, v245
	v_cvt_pk_bf16_f32 v244, v246, v247
	v_cvt_pk_bf16_f32 v245, v248, v249
	global_store_dwordx4 v181, v[242:245], s[6:7]
	s_add_u32 s6, s6, vcc_lo
	s_addc_u32 s7, s7, 0
	s_waitcnt lgkmcnt(0)
	v_cvt_pk_bf16_f32 v0, v0, v1
	v_cvt_pk_bf16_f32 v1, v2, v3
	v_cvt_pk_bf16_f32 v2, v4, v5
	v_cvt_pk_bf16_f32 v3, v6, v7
	global_store_dwordx4 v181, v[0:3], s[6:7]
	s_add_i32 s16, s16, s48
	s_cmpk_lt_u32 s16, 0x3e80
	s_cbranch_scc1 .Lmytail_loop

; #define LAS __attribute__((address_space(3)))
; template <bool MASK>
; DI void attn_unit(LAS unsigned char* lds, const bf16_t* qrow, const bf16_t* kbase, int kpitch, const bf16_t* vtbase, int vtpitch, int ntiles,
;                   const unsigned long long* maskp, bf16_t* orow, float c1, float c2) {
;     ...
;     bf16x8 qf[8];
; #pragma unroll
;     for (int ks = 0; ks < 8; ++ks) qf[ks] = *(const bf16x8*)(qrow + 16 * ks + 8 * h);
;     f32x16 o[4];
; #pragma unroll
;     for (int d = 0; d < 4; ++d)
; #pragma unroll
;         for (int i = 0; i < 16; ++i) o[d][i] = 0.f;
;     float l = 0.f;
;     u32x4 pk[2], pv[2];
;     const int ke0 = tid, ke1 = tid + 512;
;     const bf16_t* kg0 = kbase + (size_t)(ke0 >> 4) * kpitch + (ke0 & 15) * 8; const bf16_t* kg1 = kbase + (size_t)(ke1 >> 4) * kpitch + (ke1 & 15) * 8;
;     const int kl0 = (ke0 >> 4) * AK_PITCH + (ke0 & 15) * 16, kl1 = (ke1 >> 4) * AK_PITCH + (ke1 & 15) * 16;
;     const bf16_t* vg0 = vtbase + (size_t)(ke0 >> 3) * vtpitch + (ke0 & 7) * 8; const bf16_t* vg1 = vtbase + (size_t)(ke1 >> 3) * vtpitch + (ke1 & 7) * 8;
;     const int vl0 = AK_BYTES + (ke0 >> 3) * AV_PITCH + (ke0 & 7) * 16, vl1 = AK_BYTES + (ke1 >> 3) * AV_PITCH + (ke1 & 7) * 16;
;     pk[0] = *(const u32x4*)kg0; pk[1] = *(const u32x4*)kg1; pv[0] = *(const u32x4*)vg0; pv[1] = *(const u32x4*)vg1;
;     {
;         LAS unsigned char* nb = lds;
;         *(LAS u32x4*)(nb + kl0) = pk[0]; *(LAS u32x4*)(nb + kl1) = pk[1];
;         *(LAS u32x2*)(nb + vl0) = (u32x2){pv[0].x, pv[0].y}; *(LAS u32x2*)(nb + vl0 + 8) = (u32x2){pv[0].z, pv[0].w};
;         *(LAS u32x2*)(nb + vl1) = (u32x2){pv[1].x, pv[1].y}; *(LAS u32x2*)(nb + vl1 + 8) = (u32x2){pv[1].z, pv[1].w};
;     }
;     unsigned long long mw_next = ~0ull;
;     if (MASK) mw_next = maskp[0];
;     __syncthreads();
.LBB0_1243:
	v_mov_b32_e32 v63, 0
	s_andn2_b64 vcc, exec, s[2:3]
	v_mov_b32_e32 v62, v63
	v_mov_b32_e32 v61, v63
	v_mov_b32_e32 v60, v63
	v_mov_b32_e32 v59, v63
	v_mov_b32_e32 v58, v63
	v_mov_b32_e32 v57, v63
	v_mov_b32_e32 v56, v63
	v_mov_b32_e32 v55, v63
	v_mov_b32_e32 v54, v63
	v_mov_b32_e32 v53, v63
	v_mov_b32_e32 v52, v63
	v_mov_b32_e32 v51, v63
	v_mov_b32_e32 v50, v63
	v_mov_b32_e32 v49, v63
	v_mov_b32_e32 v48, v63
	v_mov_b32_e32 v47, v63
	v_mov_b32_e32 v46, v63
	v_mov_b32_e32 v45, v63
	v_mov_b32_e32 v44, v63
	v_mov_b32_e32 v43, v63
	v_mov_b32_e32 v42, v63
	v_mov_b32_e32 v41, v63
	v_mov_b32_e32 v40, v63
	v_mov_b32_e32 v39, v63
	v_mov_b32_e32 v38, v63
	v_mov_b32_e32 v37, v63
	v_mov_b32_e32 v36, v63
	v_mov_b32_e32 v35, v63
	v_mov_b32_e32 v34, v63
	v_mov_b32_e32 v33, v63
	v_mov_b32_e32 v32, v63
	v_mov_b32_e32 v31, v63
	v_mov_b32_e32 v30, v63
	v_mov_b32_e32 v29, v63
	v_mov_b32_e32 v28, v63
	v_mov_b32_e32 v27, v63
	v_mov_b32_e32 v26, v63
	v_mov_b32_e32 v25, v63
	v_mov_b32_e32 v24, v63
	v_mov_b32_e32 v23, v63
	v_mov_b32_e32 v22, v63
	v_mov_b32_e32 v21, v63
	v_mov_b32_e32 v20, v63
	v_mov_b32_e32 v19, v63
	v_mov_b32_e32 v18, v63
	v_mov_b32_e32 v17, v63
	v_mov_b32_e32 v16, v63
	v_mov_b32_e32 v15, v63
	v_mov_b32_e32 v14, v63
	v_mov_b32_e32 v13, v63
	v_mov_b32_e32 v12, v63
	v_mov_b32_e32 v11, v63
	v_mov_b32_e32 v10, v63
	v_mov_b32_e32 v9, v63
	v_mov_b32_e32 v8, v63
	v_mov_b32_e32 v7, v63
	v_mov_b32_e32 v6, v63
	v_mov_b32_e32 v5, v63
	v_mov_b32_e32 v4, v63
	v_mov_b32_e32 v3, v63
	v_mov_b32_e32 v2, v63
	v_mov_b32_e32 v1, v63
	v_mov_b32_e32 v0, v63
	v_mov_b32_e32 v149, v63
	s_mov_b64 s[30:31], 0x8000
	s_cbranch_vccnz .LBB0_1238
	s_add_i32 s17, s16, 1
	s_add_u32 s2, s18, s22
	s_addc_u32 s3, 0, 0
	s_add_u32 s2, s2, 0x20908000
	v_and_b32_e32 v0, 31, v65
	s_addc_u32 s3, s3, 0
	v_and_b32_e32 v2, 15, v65
	v_mul_u32_u24_e32 v153, 0x110, v0
	v_mul_u32_u24_e32 v180, 0x88, v0
	v_lshl_add_u64 v[0:1], s[2:3], 0, v[68:69]
	v_lshlrev_b32_e32 v2, 4, v2
	v_mov_b32_e32 v3, v161
	v_lshl_add_u64 v[154:155], v[0:1], 0, v[2:3]
	v_lshl_add_u64 v[0:1], s[2:3], 0, v[70:71]
	s_add_u32 s2, s19, 0x21100080
	v_lshl_add_u64 v[156:157], v[0:1], 0, v[2:3]
	s_addc_u32 s3, 0, 0
	v_and_b32_e32 v2, 7, v65
	v_lshl_add_u64 v[0:1], s[2:3], 0, v[72:73]
	v_lshlrev_b32_e32 v2, 4, v2
	v_lshl_add_u64 v[158:159], v[0:1], 0, v[2:3]
	v_lshl_add_u64 v[0:1], s[2:3], 0, v[74:75]
	s_add_u32 s2, s18, 0x23e08000
	s_addc_u32 s3, 0, 0
	v_mov_b32_e32 v149, 0
	v_lshlrev_b32_e32 v151, 3, v76
	v_lshl_add_u64 v[170:171], v[0:1], 0, v[2:3]
	v_lshl_add_u64 v[172:173], v[66:67], 3, s[2:3]
	s_mov_b32 s18, 0
	v_mov_b32_e32 v0, 0
	v_mov_b32_e32 v1, v149
	v_mov_b32_e32 v2, v149
	v_mov_b32_e32 v3, v149
	v_mov_b32_e32 v4, v149
	v_mov_b32_e32 v5, v149
	v_mov_b32_e32 v6, v149
	v_mov_b32_e32 v7, v149
	v_mov_b32_e32 v8, v149
	v_mov_b32_e32 v9, v149
	v_mov_b32_e32 v10, v149
	v_mov_b32_e32 v11, v149
	v_mov_b32_e32 v12, v149
	v_mov_b32_e32 v13, v149
	v_mov_b32_e32 v14, v149
	v_mov_b32_e32 v15, v149
	v_mov_b32_e32 v16, 0
	v_mov_b32_e32 v17, v149
	v_mov_b32_e32 v18, v149
	v_mov_b32_e32 v19, v149
	v_mov_b32_e32 v20, v149
	v_mov_b32_e32 v21, v149
	v_mov_b32_e32 v22, v149
	v_mov_b32_e32 v23, v149
	v_mov_b32_e32 v24, v149
	v_mov_b32_e32 v25, v149
	v_mov_b32_e32 v26, v149
	v_mov_b32_e32 v27, v149
	v_mov_b32_e32 v28, v149
	v_mov_b32_e32 v29, v149
	v_mov_b32_e32 v30, v149
	v_mov_b32_e32 v31, v149
	v_mov_b32_e32 v32, 0
	v_mov_b32_e32 v33, v149
	v_mov_b32_e32 v34, v149
	v_mov_b32_e32 v35, v149
	v_mov_b32_e32 v36, v149
	v_mov_b32_e32 v37, v149
	v_mov_b32_e32 v38, v149
	v_mov_b32_e32 v39, v149
	v_mov_b32_e32 v40, v149
	v_mov_b32_e32 v41, v149
	v_mov_b32_e32 v42, v149
	v_mov_b32_e32 v43, v149
	v_mov_b32_e32 v44, v149
	v_mov_b32_e32 v45, v149
	v_mov_b32_e32 v46, v149
	v_mov_b32_e32 v47, v149
	v_mov_b32_e32 v48, 0
	v_mov_b32_e32 v49, v149
	v_mov_b32_e32 v50, v149
	v_mov_b32_e32 v51, v149
	v_mov_b32_e32 v52, v149
	v_mov_b32_e32 v53, v149
	v_mov_b32_e32 v54, v149
	v_mov_b32_e32 v55, v149
	v_mov_b32_e32 v56, v149
	v_mov_b32_e32 v57, v149
	v_mov_b32_e32 v58, v149
	v_mov_b32_e32 v59, v149
	v_mov_b32_e32 v60, v149
	v_mov_b32_e32 v61, v149
	v_mov_b32_e32 v62, v149
	v_mov_b32_e32 v63, v149
	s_waitcnt vmcnt(0)
	s_cmp_lt_i32 s18, s16
	s_cselect_b64 s[2:3], -1, 0
	s_cmp_ge_i32 s18, s16
	s_cbranch_scc1 .LBB0_1247
	s_branch .LBB0_1246

; #define LAS __attribute__((address_space(3)))
; DI unsigned pk2(float lo, float hi) { f32x2 v = {lo, hi}; bf16x2_t b = __builtin_convertvector(v, bf16x2_t); return __builtin_bit_cast(unsigned, b); }
; template <bool MASK>
; DI void attn_unit(LAS unsigned char* lds, const bf16_t* qrow, const bf16_t* kbase, int kpitch, const bf16_t* vtbase, int vtpitch, int ntiles,
;                   const unsigned long long* maskp, bf16_t* orow, float c1, float c2) {
;     ...
;     for (int kt = 0; kt < ntiles; ++kt) {
;         const bool more = kt + 1 < ntiles;
;         if (more) {
;             const size_t ko = (size_t)(kt + 1) * 64 * kpitch; const int vo = (kt + 1) * 64;
;             pk[0] = *(const u32x4*)(kg0 + ko); pk[1] = *(const u32x4*)(kg1 + ko); pv[0] = *(const u32x4*)(vg0 + vo); pv[1] = *(const u32x4*)(vg1 + vo);
;         }
;         const unsigned long long mw = mw_next;
;         if (MASK && more) mw_next = maskp[(size_t)(kt + 1) * S_];
;         LAS unsigned char* buf = lds + (kt & 1) * ABUF;
;         f32x16 xs[2];
; #pragma unroll
;         for (int sub = 0; sub < 2; ++sub) {
; #pragma unroll
;             for (int i = 0; i < 16; ++i) xs[sub][i] = 0.f;
;             __builtin_amdgcn_s_setprio(1);
; #pragma unroll
;             for (int ks = 0; ks < 8; ++ks) {
;                 const bf16x8 a = *(const LAS bf16x8*)(buf + (32 * sub + r) * AK_PITCH + ks * 32 + h * 16);
;                 xs[sub] = __builtin_amdgcn_mfma_f32_32x32x16_bf16(a, qf[ks], xs[sub], 0, 0, 0);
;             }
;             __builtin_amdgcn_s_setprio(0);
;         }
; #pragma unroll
;         for (int sub = 0; sub < 2; ++sub) {
;             const unsigned mws = ((unsigned)(mw >> (32 * sub))) >> (4 * h);
;             float pe[16];
; #pragma unroll
;             for (int i = 0; i < 16; ++i) {
;                 float p = __builtin_amdgcn_exp2f(xs[sub][i] * c1 - c2);
;                 if (MASK) { const int m = __builtin_amdgcn_sbfe((int)mws, (i & 3) + 8 * (i >> 2), 1); p = __uint_as_float(__float_as_uint(p) & (unsigned)m); }
;                 l += p; pe[i] = p;
;             }
;             u32x4 p0, p1;
;             p0.x = pk2(pe[0], pe[1]); p0.y = pk2(pe[2], pe[3]); p0.z = pk2(pe[4], pe[5]); p0.w = pk2(pe[6], pe[7]);
;             p1.x = pk2(pe[8], pe[9]); p1.y = pk2(pe[10], pe[11]); p1.z = pk2(pe[12], pe[13]); p1.w = pk2(pe[14], pe[15]);
.LBB0_1246:
	v_lshl_add_u64 v[64:65], s[0:1], 0, v[154:155]
	v_lshl_add_u64 v[66:67], s[0:1], 0, v[156:157]
	v_lshl_add_u64 v[68:69], s[0:1], 0, v[158:159]
	v_lshl_add_u64 v[70:71], s[0:1], 0, v[170:171]
	global_load_dwordx4 v[96:99], v[64:65], off
	global_load_dwordx4 v[100:103], v[66:67], off
	global_load_dwordx4 v[104:107], v[68:69], off
	global_load_dwordx4 v[108:111], v[70:71], off
.LBB0_1247:
	v_cndmask_b32_e64 v64, 0, 1, s[2:3]
	v_cmp_ne_u32_e64 s[38:39], 1, v64
	s_andn2_b64 vcc, exec, s[2:3]
	v_mov_b64_e32 v[174:175], v[176:177]
	s_cbranch_vccnz .LBB0_1249
	v_lshl_add_u64 v[64:65], s[0:1], 0, v[172:173]
	global_load_dwordx2 v[174:175], v[64:65], off
.LBB0_1249:
	s_add_i32 s2, s18, 1
	s_bitcmp1_b32 s18, 0
	s_cselect_b32 s3, 0x8800, 0
	s_add_i32 s3, s3, 0
	s_setprio 1
	v_add3_u32 v166, s3, v160, v153
	ds_read_b128 v[212:215], v166
	ds_read_b128 v[216:219], v166 offset:32
	ds_read_b128 v[220:223], v166 offset:64
	ds_read_b128 v[224:227], v166 offset:96
	ds_read_b128 v[228:231], v166 offset:128
	ds_read_b128 v[232:235], v166 offset:160
	ds_read_b128 v[236:239], v166 offset:192
	ds_read_b128 v[240:243], v166 offset:224
	ds_read_b128 v[244:247], v166 offset:8704
	ds_read_b128 v[248:251], v166 offset:8736
	ds_read_b128 v[200:203], v166 offset:8768
	ds_read_b128 v[204:207], v166 offset:8800
	ds_read_b128 v[208:211], v166 offset:8832
	ds_read_b128 v[182:185], v166 offset:8864
	s_waitcnt lgkmcnt(13)
	v_mfma_f32_32x32x16_bf16 v[80:95], v[212:215], v[112:115], 0
	s_waitcnt lgkmcnt(12)
	v_mfma_f32_32x32x16_bf16 v[80:95], v[216:219], v[116:119], v[80:95]
	ds_read_b128 v[212:215], v166 offset:8896
	ds_read_b128 v[216:219], v166 offset:8928
	s_waitcnt lgkmcnt(13)
	v_mfma_f32_32x32x16_bf16 v[80:95], v[220:223], v[120:123], v[80:95]
	s_waitcnt lgkmcnt(12)
	v_mfma_f32_32x32x16_bf16 v[80:95], v[224:227], v[124:127], v[80:95]
	s_waitcnt lgkmcnt(11)
	v_mfma_f32_32x32x16_bf16 v[80:95], v[228:231], v[128:131], v[80:95]
	s_waitcnt lgkmcnt(10)
	v_mfma_f32_32x32x16_bf16 v[80:95], v[232:235], v[132:135], v[80:95]
	s_waitcnt lgkmcnt(9)
	v_mfma_f32_32x32x16_bf16 v[80:95], v[236:239], v[136:139], v[80:95]
	s_waitcnt lgkmcnt(8)
	v_mfma_f32_32x32x16_bf16 v[80:95], v[240:243], v[140:143], v[80:95]
	s_waitcnt lgkmcnt(7)
	v_mfma_f32_32x32x16_bf16 v[64:79], v[244:247], v[112:115], 0
	s_waitcnt lgkmcnt(6)
	v_mfma_f32_32x32x16_bf16 v[64:79], v[248:251], v[116:119], v[64:79]
	s_waitcnt lgkmcnt(5)
	v_mfma_f32_32x32x16_bf16 v[64:79], v[200:203], v[120:123], v[64:79]
	s_waitcnt lgkmcnt(4)
	v_mfma_f32_32x32x16_bf16 v[64:79], v[204:207], v[124:127], v[64:79]
	s_waitcnt lgkmcnt(3)
	v_mfma_f32_32x32x16_bf16 v[64:79], v[208:211], v[128:131], v[64:79]
	s_waitcnt lgkmcnt(2)
	v_mfma_f32_32x32x16_bf16 v[64:79], v[182:185], v[132:135], v[64:79]
	s_waitcnt lgkmcnt(1)
	v_mfma_f32_32x32x16_bf16 v[64:79], v[212:215], v[136:139], v[64:79]
	s_waitcnt lgkmcnt(0)
	v_mfma_f32_32x32x16_bf16 v[64:79], v[216:219], v[140:143], v[64:79]
	s_setprio 0
	v_add3_u32 v166, s3, v151, v180
	v_lshrrev_b32_e32 v204, v147, v176
	v_lshrrev_b32_e32 v205, v147, v177
	v_add_u32_e32 v167, 0x4000, v166
	v_add_u32_e32 v168, 0x5000, v166
	v_add_u32_e32 v169, 0x6000, v166
	v_add_u32_e32 v199, 0x7000, v166
	ds_read2_b64 v[220:223], v167 offset0:128 offset1:130
	ds_read2_b64 v[224:227], v167 offset0:132 offset1:134
	ds_read2_b64 v[228:231], v168 offset0:160 offset1:162
	ds_read2_b64 v[232:235], v168 offset0:164 offset1:166
	ds_read2_b64 v[236:239], v169 offset0:192 offset1:194
	ds_read2_b64 v[240:243], v169 offset0:196 offset1:198
	ds_read2_b64 v[244:247], v199 offset0:224 offset1:226
	ds_read2_b64 v[248:251], v199 offset0:228 offset1:230
	v_fma_f32 v80, v80, s95, -v178
	v_exp_f32_e32 v80, v80
	v_bfe_i32 v206, v204, 0, 1
	v_fma_f32 v81, v81, s95, -v178
	v_exp_f32_e32 v81, v81
	v_bfe_i32 v207, v204, 1, 1
	v_and_b32_e32 v80, v80, v206
	v_fma_f32 v82, v82, s95, -v178
	v_exp_f32_e32 v82, v82
	v_bfe_i32 v208, v204, 2, 1
	v_and_b32_e32 v81, v81, v207
	v_fma_f32 v83, v83, s95, -v178
	v_exp_f32_e32 v83, v83
	v_bfe_i32 v209, v204, 3, 1
	v_and_b32_e32 v82, v82, v208
	v_fma_f32 v84, v84, s95, -v178
	v_exp_f32_e32 v84, v84
	v_bfe_i32 v210, v204, 8, 1
	v_and_b32_e32 v83, v83, v209
	v_fma_f32 v85, v85, s95, -v178
	v_exp_f32_e32 v85, v85
	v_bfe_i32 v211, v204, 9, 1
	v_and_b32_e32 v84, v84, v210
	v_fma_f32 v86, v86, s95, -v178
	v_exp_f32_e32 v86, v86
	v_bfe_i32 v206, v204, 10, 1
	v_and_b32_e32 v85, v85, v211
	v_fma_f32 v87, v87, s95, -v178
	v_exp_f32_e32 v87, v87
	v_bfe_i32 v207, v204, 11, 1
	v_and_b32_e32 v86, v86, v206
	v_fma_f32 v88, v88, s95, -v178
	v_exp_f32_e32 v88, v88
	v_bfe_i32 v208, v204, 16, 1
	v_and_b32_e32 v87, v87, v207
	v_fma_f32 v89, v89, s95, -v178
	v_exp_f32_e32 v89, v89
	v_bfe_i32 v209, v204, 17, 1
	v_and_b32_e32 v88, v88, v208
	v_fma_f32 v90, v90, s95, -v178
	v_exp_f32_e32 v90, v90
	v_bfe_i32 v210, v204, 18, 1
	v_and_b32_e32 v89, v89, v209
	v_fma_f32 v91, v91, s95, -v178
	v_exp_f32_e32 v91, v91
	v_bfe_i32 v211, v204, 19, 1
	v_and_b32_e32 v90, v90, v210
	v_fma_f32 v92, v92, s95, -v178
	v_exp_f32_e32 v92, v92
	v_bfe_i32 v206, v204, 24, 1
	v_and_b32_e32 v91, v91, v211
	v_fma_f32 v93, v93, s95, -v178
	v_exp_f32_e32 v93, v93
	v_bfe_i32 v207, v204, 25, 1
	v_and_b32_e32 v92, v92, v206
	v_fma_f32 v94, v94, s95, -v178
	v_exp_f32_e32 v94, v94
	v_bfe_i32 v208, v204, 26, 1
	v_and_b32_e32 v93, v93, v207
	v_fma_f32 v95, v95, s95, -v178
	v_exp_f32_e32 v95, v95
	v_bfe_i32 v209, v204, 27, 1
	v_and_b32_e32 v94, v94, v208
	v_nop
	v_and_b32_e32 v95, v95, v209
	v_cvt_pk_bf16_f32 v182, v80, v81
	v_cvt_pk_bf16_f32 v183, v82, v83
	v_cvt_pk_bf16_f32 v184, v84, v85
	v_cvt_pk_bf16_f32 v185, v86, v87
	v_cvt_pk_bf16_f32 v200, v88, v89
	v_cvt_pk_bf16_f32 v201, v90, v91
	v_cvt_pk_bf16_f32 v202, v92, v93
	v_cvt_pk_bf16_f32 v203, v94, v95
	v_pk_add_f32 v[80:81], v[80:81], v[82:83]
	v_pk_add_f32 v[84:85], v[84:85], v[86:87]
	v_pk_add_f32 v[88:89], v[88:89], v[90:91]
	v_pk_add_f32 v[92:93], v[92:93], v[94:95]
	v_pk_add_f32 v[80:81], v[80:81], v[84:85]
	v_pk_add_f32 v[88:89], v[88:89], v[92:93]
	v_pk_add_f32 v[80:81], v[80:81], v[88:89]
	v_add_f32_e32 v80, v80, v81
	v_add_f32_e32 v149, v149, v80
	s_waitcnt lgkmcnt(0)
; template <bool MASK>
; DI void attn_unit(LAS unsigned char* lds, const bf16_t* qrow, const bf16_t* kbase, int kpitch, const bf16_t* vtbase, int vtpitch, int ntiles,
;                   const unsigned long long* maskp, bf16_t* orow, float c1, float c2) {
;     ...
;         for (int sub = 0; sub < 2; ++sub) {
;             const unsigned mws = ((unsigned)(mw >> (32 * sub))) >> (4 * h);
;             float pe[16];
; #pragma unroll
;             for (int i = 0; i < 16; ++i) {
;                 float p = __builtin_amdgcn_exp2f(xs[sub][i] * c1 - c2);
;                 if (MASK) { const int m = __builtin_amdgcn_sbfe((int)mws, (i & 3) + 8 * (i >> 2), 1); p = __uint_as_float(__float_as_uint(p) & (unsigned)m); }
;                 l += p; pe[i] = p;
;             }
;             u32x4 p0, p1;
;             p0.x = pk2(pe[0], pe[1]); p0.y = pk2(pe[2], pe[3]); p0.z = pk2(pe[4], pe[5]); p0.w = pk2(pe[6], pe[7]);
;             p1.x = pk2(pe[8], pe[9]); p1.y = pk2(pe[10], pe[11]); p1.z = pk2(pe[12], pe[13]); p1.w = pk2(pe[14], pe[15]);
;             const bf16x8 pb0 = __builtin_bit_cast(bf16x8, p0), pb1 = __builtin_bit_cast(bf16x8, p1);
; #pragma unroll
;             for (int dt = 0; dt < 4; ++dt) {
;                 const LAS unsigned char* vp = buf + AK_BYTES + (32 * dt + r) * AV_PITCH + (32 * sub + 4 * h) * 2;
;                 const s16x4 lo0 = *(const LAS s16x4*)(vp), hi0 = *(const LAS s16x4*)(vp + 16);
;                 const s16x4 lo1 = *(const LAS s16x4*)(vp + 32), hi1 = *(const LAS s16x4*)(vp + 48);
;                 const bf16x8 va0 = __builtin_shufflevector(lo0, hi0, 0, 1, 2, 3, 4, 5, 6, 7);
;                 const bf16x8 va1 = __builtin_shufflevector(lo1, hi1, 0, 1, 2, 3, 4, 5, 6, 7);
;                 o[dt] = __builtin_amdgcn_mfma_f32_32x32x16_bf16(va0, pb0, o[dt], 0, 0, 0);
;                 o[dt] = __builtin_amdgcn_mfma_f32_32x32x16_bf16(va1, pb1, o[dt], 0, 0, 0);
;             }
;         }
;         if (more) {
;             LAS unsigned char* nb = lds + ((kt + 1) & 1) * ABUF;
;             *(LAS u32x4*)(nb + kl0) = pk[0]; *(LAS u32x4*)(nb + kl1) = pk[1];
;             *(LAS u32x2*)(nb + vl0) = (u32x2){pv[0].x, pv[0].y}; *(LAS u32x2*)(nb + vl0 + 8) = (u32x2){pv[0].z, pv[0].w};
;             *(LAS u32x2*)(nb + vl1) = (u32x2){pv[1].x, pv[1].y}; *(LAS u32x2*)(nb + vl1 + 8) = (u32x2){pv[1].z, pv[1].w};
;         }
;         __syncthreads();
	v_mfma_f32_32x32x16_bf16 v[48:63], v[220:223], v[182:185], v[48:63]
	v_fma_f32 v64, v64, s95, -v178
	v_exp_f32_e32 v64, v64
	v_bfe_i32 v206, v205, 0, 1
	v_fma_f32 v65, v65, s95, -v178
	v_exp_f32_e32 v65, v65
	v_bfe_i32 v207, v205, 1, 1
	v_and_b32_e32 v64, v64, v206
	v_mfma_f32_32x32x16_bf16 v[48:63], v[224:227], v[200:203], v[48:63]
	v_fma_f32 v66, v66, s95, -v178
	v_exp_f32_e32 v66, v66
	v_bfe_i32 v208, v205, 2, 1
	v_and_b32_e32 v65, v65, v207
	v_fma_f32 v67, v67, s95, -v178
	v_exp_f32_e32 v67, v67
	v_bfe_i32 v209, v205, 3, 1
	v_mfma_f32_32x32x16_bf16 v[32:47], v[228:231], v[182:185], v[32:47]
	v_and_b32_e32 v66, v66, v208
	v_fma_f32 v68, v68, s95, -v178
	v_exp_f32_e32 v68, v68
	v_bfe_i32 v210, v205, 8, 1
	v_and_b32_e32 v67, v67, v209
	v_fma_f32 v69, v69, s95, -v178
	v_exp_f32_e32 v69, v69
	v_mfma_f32_32x32x16_bf16 v[32:47], v[232:235], v[200:203], v[32:47]
	v_bfe_i32 v211, v205, 9, 1
	v_and_b32_e32 v68, v68, v210
	v_fma_f32 v70, v70, s95, -v178
	v_exp_f32_e32 v70, v70
	v_bfe_i32 v206, v205, 10, 1
	v_and_b32_e32 v69, v69, v211
	v_fma_f32 v71, v71, s95, -v178
	v_mfma_f32_32x32x16_bf16 v[16:31], v[236:239], v[182:185], v[16:31]
	v_exp_f32_e32 v71, v71
	v_bfe_i32 v207, v205, 11, 1
	v_and_b32_e32 v70, v70, v206
	v_fma_f32 v72, v72, s95, -v178
	v_exp_f32_e32 v72, v72
	v_bfe_i32 v208, v205, 16, 1
	v_and_b32_e32 v71, v71, v207
	v_mfma_f32_32x32x16_bf16 v[16:31], v[240:243], v[200:203], v[16:31]
	v_fma_f32 v73, v73, s95, -v178
	v_exp_f32_e32 v73, v73
	v_bfe_i32 v209, v205, 17, 1
	v_and_b32_e32 v72, v72, v208
	v_fma_f32 v74, v74, s95, -v178
	v_exp_f32_e32 v74, v74
	v_bfe_i32 v210, v205, 18, 1
	v_mfma_f32_32x32x16_bf16 v[0:15], v[244:247], v[182:185], v[0:15]
	v_and_b32_e32 v73, v73, v209
	v_fma_f32 v75, v75, s95, -v178
	v_exp_f32_e32 v75, v75
	v_bfe_i32 v211, v205, 19, 1
	v_and_b32_e32 v74, v74, v210
	v_fma_f32 v76, v76, s95, -v178
	v_exp_f32_e32 v76, v76
	v_mfma_f32_32x32x16_bf16 v[0:15], v[248:251], v[200:203], v[0:15]
	ds_read2_b64 v[220:223], v167 offset0:136 offset1:138
	ds_read2_b64 v[224:227], v167 offset0:140 offset1:142
	ds_read2_b64 v[228:231], v168 offset0:168 offset1:170
	ds_read2_b64 v[232:235], v168 offset0:172 offset1:174
	ds_read2_b64 v[236:239], v169 offset0:200 offset1:202
	ds_read2_b64 v[240:243], v169 offset0:204 offset1:206
	ds_read2_b64 v[244:247], v199 offset0:232 offset1:234
	ds_read2_b64 v[248:251], v199 offset0:236 offset1:238
	v_bfe_i32 v206, v205, 24, 1
	v_and_b32_e32 v75, v75, v211
	v_fma_f32 v77, v77, s95, -v178
	v_exp_f32_e32 v77, v77
	v_bfe_i32 v207, v205, 25, 1
	v_and_b32_e32 v76, v76, v206
	v_fma_f32 v78, v78, s95, -v178
	v_exp_f32_e32 v78, v78
	v_bfe_i32 v208, v205, 26, 1
	v_and_b32_e32 v77, v77, v207
	v_fma_f32 v79, v79, s95, -v178
	v_exp_f32_e32 v79, v79
	v_bfe_i32 v209, v205, 27, 1
	v_and_b32_e32 v78, v78, v208
	v_nop
	v_and_b32_e32 v79, v79, v209
	v_cvt_pk_bf16_f32 v212, v64, v65
	v_cvt_pk_bf16_f32 v213, v66, v67
	v_cvt_pk_bf16_f32 v214, v68, v69
	v_cvt_pk_bf16_f32 v215, v70, v71
	v_cvt_pk_bf16_f32 v216, v72, v73
	v_cvt_pk_bf16_f32 v217, v74, v75
	v_cvt_pk_bf16_f32 v218, v76, v77
	v_cvt_pk_bf16_f32 v219, v78, v79
	v_pk_add_f32 v[64:65], v[64:65], v[66:67]
	v_pk_add_f32 v[68:69], v[68:69], v[70:71]
	v_pk_add_f32 v[72:73], v[72:73], v[74:75]
	v_pk_add_f32 v[76:77], v[76:77], v[78:79]
	v_pk_add_f32 v[64:65], v[64:65], v[68:69]
	v_pk_add_f32 v[72:73], v[72:73], v[76:77]
	v_pk_add_f32 v[64:65], v[64:65], v[72:73]
	v_add_f32_e32 v64, v64, v65
	v_add_f32_e32 v149, v149, v64
	s_and_b64 vcc, exec, s[38:39]
	s_waitcnt lgkmcnt(0)
	v_mfma_f32_32x32x16_bf16 v[48:63], v[220:223], v[212:215], v[48:63]
	v_mfma_f32_32x32x16_bf16 v[48:63], v[224:227], v[216:219], v[48:63]
	v_mfma_f32_32x32x16_bf16 v[32:47], v[228:231], v[212:215], v[32:47]
	v_mfma_f32_32x32x16_bf16 v[32:47], v[232:235], v[216:219], v[32:47]
	v_mfma_f32_32x32x16_bf16 v[16:31], v[236:239], v[212:215], v[16:31]
	v_mfma_f32_32x32x16_bf16 v[16:31], v[240:243], v[216:219], v[16:31]
	v_mfma_f32_32x32x16_bf16 v[0:15], v[244:247], v[212:215], v[0:15]
	v_mfma_f32_32x32x16_bf16 v[0:15], v[248:251], v[216:219], v[0:15]
	s_cbranch_vccnz .LBB0_1251
	s_waitcnt vmcnt(1)
	s_bitcmp1_b32 s2, 0
	s_cselect_b32 s3, 0x8800, 0
	s_add_i32 s3, s3, 0
	v_add_u32_e32 v166, s3, v146
	ds_write_b128 v166, v[96:99]
	v_add_u32_e32 v166, s3, v148
	ds_write_b128 v166, v[100:103]
	v_add_u32_e32 v166, s3, v150
	v_add_u32_e32 v166, 0x4400, v166
	ds_write2_b64 v166, v[104:105], v[106:107] offset1:1
	v_add_u32_e32 v166, s3, v152
	v_add_u32_e32 v166, 0x4400, v166
	ds_write2_b64 v166, v[108:109], v[110:111] offset1:1
.LBB0_1251:
	v_lshl_add_u64 v[154:155], v[154:155], 0, s[30:31]
	v_lshl_add_u64 v[156:157], v[156:157], 0, s[30:31]
	v_lshl_add_u64 v[158:159], v[158:159], 0, s[78:79]
	v_lshl_add_u64 v[170:171], v[170:171], 0, s[78:79]
	s_cmp_lg_u32 s17, s2
	v_lshl_add_u64 v[172:173], v[172:173], 0, s[30:31]
	s_waitcnt lgkmcnt(0)
	s_barrier
	s_cbranch_scc1 .LBB0_1245
	v_mov_b32_e32 v64, v147
	s_branch .LBB0_1238
